# scan loops: gamma sum-of-squares shuffles via DPP instead of LDS bpermute; mlstm denominator read directly (ones-row broadcast across MFMA B columns)
# speedup vs baseline: 1.0109x; 1.0109x over previous
.LBB0_433:
	s_or_b64 exec, exec, s[0:1]
	s_mov_b32 s0, 0x3fb8aa3b
	s_waitcnt vmcnt(6)
	v_mul_f32_e64 v59, -v66, s0
	s_waitcnt lgkmcnt(6)
	v_add_f32_e32 v177, v66, v67
	global_load_dwordx4 v[64:67], v[64:65], off offset:2048
	s_bfe_u32 s1, s66, 0x30001
	s_lshr_b32 s10, s58, 6
	s_lshl_b32 s0, s1, 21
	s_lshl_b32 s11, s10, 20
	s_add_i32 s72, s0, s11
	s_lshl_b32 s0, s1, 1
	s_waitcnt vmcnt(0)
	v_ashrrev_i32_e32 v67, 7, v74
	v_lshlrev_b32_e32 v100, 1, v82
	v_exp_f32_e32 v114, v59
	v_lshrrev_b32_e32 v59, 4, v75
	s_lshl_b32 s91, s1, 14
	s_lshl_b32 s3, s10, 13
	s_add_i32 s0, s10, s0
	s_lshl_b32 s1, s1, 17
	s_lshl_b32 s10, s10, 16
	v_and_b32_e32 v104, 2, v100
	v_lshlrev_b32_e32 v100, 4, v67
	v_and_b32_e32 v73, 15, v74
	s_add_i32 s1, s1, s10
	s_and_b32 s10, s2, 7
	v_lshl_or_b32 v105, v59, 2, v100
	v_lshlrev_b32_e32 v101, 5, v67
	v_lshlrev_b32_e32 v59, 3, v59
	v_readlane_b32 s12, v250, 54
	v_and_b32_e32 v106, 48, v75
	s_lshl_b32 s10, s10, 13
	v_bfe_u32 v83, v74, 6, 1
	v_add3_u32 v117, s12, v101, v59
	v_or_b32_e32 v102, v100, v73
	v_add_u32_e32 v116, 0, v106
	s_lshl_b64 s[92:93], s[72:73], 1
	s_or_b32 s72, s1, s10
	v_mad_u64_u32 v[100:101], s[10:11], v102, s25, v[116:117]
	v_lshl_or_b32 v103, v83, 4, v73
	v_mul_lo_u32 v102, v102, s33
	v_add3_u32 v127, s12, v102, v106
	v_mul_u32_u24_e32 v102, 0x90, v103
	v_add3_u32 v128, s65, v102, v106
	v_lshl_or_b32 v102, v82, 4, v73
	v_mad_u32_u24 v101, v103, s25, v116
	v_mad_u64_u32 v[102:103], s[10:11], v102, s33, v[116:117]
	v_and_or_b32 v74, v74, 48, v80
	v_lshlrev_b32_e32 v131, 2, v74
	v_lshlrev_b32_e32 v74, 5, v83
	v_lshlrev_b32_e32 v83, 1, v73
	v_readlane_b32 s10, v250, 55
	s_movk_i32 s18, 0x50
	v_lshlrev_b32_e32 v110, 4, v78
	v_add3_u32 v74, s10, v74, v83
	v_mul_lo_u32 v83, v92, s18
	v_add3_u32 v134, s10, v83, v110
	v_cmp_eq_u32_e64 s[10:11], 0, v78
	v_mul_lo_u32 v120, v105, s18
	v_cmp_gt_u32_e64 s[18:19], 2, v78
	v_or_b32_e32 v78, v77, v76
	v_mul_u32_u24_e32 v78, 0x48, v78
	v_lshlrev_b32_e32 v82, 5, v82
	v_add_lshl_u32 v78, v92, v78, 1
	v_add3_u32 v59, 0, v82, v59
	v_lshlrev_b32_e32 v82, 2, v75
	s_add_i32 s48, 0, 0x17200
	s_add_i32 s14, 0, 0x17100
	s_add_i32 s16, 0, 0x17400
	s_add_i32 s17, 0, 0x17300
	v_add_u32_e32 v148, s65, v78
	v_add_u32_e32 v149, s64, v78
	v_add_u32_e32 v78, 0x90, v78
	v_add_u32_e32 v132, s48, v82
	v_add_u32_e32 v133, s14, v82
	v_add_u32_e32 v137, s16, v82
	v_add_u32_e32 v138, s17, v82
	v_lshlrev_b32_e32 v82, 2, v105
	v_add_u32_e32 v150, s65, v78
	v_add_u32_e32 v151, s64, v78
	v_add_u32_e32 v78, 2, v77
	v_add_u32_e32 v146, s17, v82
	v_add_u32_e32 v147, s16, v82
	v_cmp_eq_u32_e64 s[16:17], 0, v79
	v_and_b32_e32 v79, 4, v78
	v_and_or_b32 v78, v78, 6, v76
	v_mul_u32_u24_e32 v78, 0x48, v78
	v_add_lshl_u32 v78, v92, v78, 1
	v_add_u32_e32 v152, s65, v78
	v_add_u32_e32 v153, s64, v78
	v_add_u32_e32 v78, 3, v77
	v_cmp_eq_u32_e64 s[20:21], 0, v79
	v_and_b32_e32 v79, 2, v78
	v_cmp_eq_u32_e64 s[22:23], 0, v79
	v_and_b32_e32 v79, 4, v78
	v_and_or_b32 v78, v78, 7, v76
	v_mul_u32_u24_e32 v78, 0x48, v78
	v_mul_u32_u24_e32 v129, 0x90, v73
	v_add_lshl_u32 v78, v92, v78, 1
	v_add3_u32 v130, s65, v129, v106
	v_add_u32_e32 v254, s65, v106
	v_add_u32_e32 v103, s64, v106
	v_xor_b32_e32 v83, 1, v123
	v_add_u32_e32 v106, 64, v80
	v_add_u32_e32 v154, s65, v78
	v_add_u32_e32 v155, s64, v78
	v_bitop3_b32 v78, v77, 4, v76 bitop3:0x36
	v_cmp_lt_i32_e32 vcc, v83, v106
	v_mul_u32_u24_e32 v78, 0x48, v78
	v_add_lshl_u32 v78, v92, v78, 1
	v_cndmask_b32_e32 v83, v123, v83, vcc
	v_lshlrev_b32_e32 v135, 2, v83
	v_xor_b32_e32 v83, 2, v123
	v_add_u32_e32 v156, s65, v78
	v_add_u32_e32 v157, s64, v78
	v_add_u32_e32 v78, 5, v77
	v_mad_u32_u24 v115, v73, s25, v116
	v_mov_b32_e32 v253, v116
	v_cmp_lt_i32_e32 vcc, v83, v106
	v_cmp_eq_u32_e64 s[24:25], 0, v79
	v_and_b32_e32 v79, 2, v78
	v_cndmask_b32_e32 v83, v123, v83, vcc
	v_and_or_b32 v80, v92, 63, v80
	v_cmp_eq_u32_e64 s[26:27], 0, v79
	v_and_b32_e32 v79, 4, v78
	v_and_or_b32 v78, v78, 7, v76
	s_lshl_b32 s0, s0, 10
	v_lshlrev_b32_e32 v136, 2, v83
	v_lshlrev_b32_e32 v139, 2, v80
	v_cmp_le_i32_e64 s[12:13], v67, v104
	v_lshl_or_b32 v80, v104, 4, v73
	v_or_b32_e32 v83, 2, v105
	v_or_b32_e32 v106, 3, v105
	v_or_b32_e32 v104, 1, v104
	v_mul_u32_u24_e32 v78, 0x48, v78
	s_and_b32 s0, s0, 0xffffe000
	s_mov_b32 s1, s73
	v_add_u32_e32 v142, s14, v82
	v_lshl_add_u32 v144, v83, 2, s14
	v_lshl_add_u32 v145, v106, 2, s14
	v_cmp_le_i32_e64 s[14:15], v67, v104
	v_lshl_or_b32 v67, v104, 4, v73
	v_add_lshl_u32 v78, v92, v78, 1
	v_add_u32_e32 v158, s65, v78
	v_add_u32_e32 v159, s64, v78
	v_add_u32_e32 v78, 6, v77
	v_cmp_le_i32_e64 s[46:47], v106, v80
	v_cmp_le_i32_e64 s[54:55], v106, v67
	v_lshl_add_u64 v[106:107], v[68:69], 1, s[92:93]
	v_lshl_add_u64 v[68:69], v[92:93], 0, s[0:1]
	v_cmp_eq_u32_e64 s[28:29], 0, v79
	v_and_b32_e32 v79, 2, v78
	v_lshl_add_u32 v166, v80, 2, s48
	v_cmp_le_i32_e64 s[40:41], v105, v80
	v_cmp_lt_i32_e64 s[42:43], v105, v80
	v_lshl_add_u32 v167, v67, 2, s48
	v_cmp_le_i32_e64 s[48:49], v105, v67
	v_cmp_lt_i32_e64 s[50:51], v105, v67
	v_lshl_add_u64 v[104:105], v[70:71], 1, s[92:93]
	v_mad_u64_u32 v[70:71], s[92:93], v68, s96, 0
	v_cmp_eq_u32_e64 s[30:31], 0, v79
	v_and_b32_e32 v79, 4, v78
	v_and_or_b32 v78, v78, 6, v76
	v_add_u32_e32 v77, 7, v77
	v_mov_b32_e32 v68, v71
	v_mul_u32_u24_e32 v78, 0x48, v78
	v_and_or_b32 v76, v77, 7, v76
	v_mad_u64_u32 v[68:69], s[92:93], v69, s96, v[68:69]
	v_add_lshl_u32 v78, v92, v78, 1
	v_mul_u32_u24_e32 v76, 0x48, v76
	v_or_b32_e32 v70, v70, v110
	v_mov_b32_e32 v71, v68
	v_mul_u32_u24_e32 v118, 0x110, v73
	v_or_b32_e32 v73, 16, v73
	v_add_u32_e32 v160, s65, v78
	v_add_u32_e32 v161, s64, v78
	v_and_b32_e32 v78, 2, v77
	v_add_lshl_u32 v76, v92, v76, 1
	v_lshl_add_u64 v[68:69], v[98:99], 1, v[70:71]
	v_lshlrev_b32_e32 v110, 1, v72
	v_mov_b32_e32 v111, v85
	s_lshl_b64 s[94:95], s[72:73], 2
	v_add_u32_e32 v140, s64, v81
	v_add_u32_e32 v141, s65, v81
	v_mul_u32_u24_e32 v81, 0x110, v80
	v_mul_u32_u24_e32 v119, 0x110, v67
	v_mul_u32_u24_e32 v82, 0x90, v73
	v_mul_u32_u24_e32 v73, 0x110, v73
	v_cmp_eq_u32_e64 s[36:37], 0, v78
	v_and_b32_e32 v78, 4, v77
	v_add_u32_e32 v162, s65, v76
	v_add_u32_e32 v163, s64, v76
	v_mul_u32_u24_e32 v76, 0x90, v80
	v_cmp_le_i32_e64 s[52:53], v83, v67
	v_mul_u32_u24_e32 v67, 0x90, v67
	s_add_i32 s91, s91, s3
	v_lshl_add_u64 v[112:113], v[68:69], 0, v[110:111]
	v_mov_b32_e32 v68, 0
	s_mov_b32 s62, 0
	v_add_u32_e32 v143, 4, v142
	v_cmp_eq_u32_e64 s[34:35], 0, v79
	v_cmp_eq_u32_e64 s[38:39], 0, v78
	v_cmp_le_i32_e64 s[44:45], v83, v80
	v_or_b32_e32 v168, s91, v75
	v_lshl_add_u64 v[108:109], v[92:93], 2, s[94:95]
	v_add_u32_e32 v169, v116, v81
	v_add_u32_e32 v170, v117, v76
	v_add_u32_e32 v171, v116, v119
	v_add_u32_e32 v172, v117, v67
	v_add_u32_e32 v173, v103, v82
	v_add_u32_e32 v174, v74, v120
	v_add_u32_e32 v175, v59, v118
	v_add_u32_e32 v176, v59, v73
	s_mov_b32 s1, 0
	v_mov_b32_e32 v69, v68
	v_mov_b32_e32 v70, v68
	v_mov_b32_e32 v71, v68
	v_mov_b32_e32 v72, v68
	v_mov_b32_e32 v73, v68
	v_mov_b32_e32 v74, v68
	v_mov_b32_e32 v75, v68
	v_mov_b32_e32 v76, v68
	v_mov_b32_e32 v77, v68
	v_mov_b32_e32 v78, v68
	v_mov_b32_e32 v79, v68
	s_waitcnt lgkmcnt(0)
	s_barrier
	s_branch .LBB0_436

.LBB0_454:
	s_or_b64 exec, exec, s[92:93]
	v_perm_b32 v82, v111, v251, s97
	v_perm_b32 v83, v81, v80, s97
	ds_write_b64 v172, v[82:83]
	ds_read_b128 v[80:83], v100
	ds_read_b128 v[116:119], v101 offset:34816
	ds_read_b128 v[178:181], v100 offset:64
	ds_read_b128 v[182:185], v101 offset:34880
	ds_read_b128 v[186:189], v253 offset:43520
	ds_read_b128 v[190:193], v253 offset:43584
	s_waitcnt lgkmcnt(4)
	v_mfma_f32_16x16x32_bf16 v[116:119], v[80:83], v[116:119], 0
	v_mul_f32_e64 v70, v70, v114
	v_mul_f32_e64 v71, v71, v114
	v_pk_mul_f32 v[68:69], v[68:69], v[114:115] op_sel_hi:[1,0]
	v_pk_mul_f32 v[78:79], v[78:79], v[114:115] op_sel_hi:[1,0]
	s_waitcnt lgkmcnt(2)
	v_mfma_f32_16x16x32_bf16 v[116:119], v[178:181], v[182:185], v[116:119]
	ds_read_b128 v[182:185], v100 offset:128
	v_pk_mul_f32 v[76:77], v[76:77], v[114:115] op_sel_hi:[1,0]
	v_pk_mul_f32 v[74:75], v[74:75], v[114:115] op_sel_hi:[1,0]
	s_waitcnt lgkmcnt(2)
	v_mfma_f32_16x16x32_bf16 v[80:83], v[80:83], v[186:189], 0
	v_mul_f32_e64 v72, v72, v114
	v_mul_f32_e64 v73, v73, v114
	s_waitcnt lgkmcnt(1)
	v_mfma_f32_16x16x32_bf16 v[80:83], v[178:181], v[190:193], v[80:83]
	ds_read_b128 v[178:181], v101 offset:34944
	ds_read_b128 v[186:189], v100 offset:192
	ds_read_b128 v[190:193], v101 offset:35008
	s_waitcnt lgkmcnt(2)
	v_mfma_f32_16x16x32_bf16 v[116:119], v[182:185], v[178:181], v[116:119]
	ds_read_b128 v[178:181], v253 offset:43648
	ds_read_b128 v[194:197], v253 offset:43712
	s_waitcnt lgkmcnt(0)
	s_barrier
	v_mfma_f32_16x16x32_bf16 v[80:83], v[182:185], v[178:181], v[80:83]
	ds_read_b128 v[178:181], v146
	ds_read_b128 v[182:185], v147
	v_mfma_f32_16x16x32_bf16 v[80:83], v[186:189], v[194:197], v[80:83]
	s_waitcnt lgkmcnt(0)
	v_max_f32_e32 v252, v182, v182
	v_mfma_f32_16x16x32_bf16 v[116:119], v[186:189], v[190:193], v[116:119]
	ds_read_b128 v[186:189], v127
	ds_read_b128 v[190:193], v127 offset:64
	ds_read_b128 v[194:197], v128
	ds_read_b128 v[198:201], v128 offset:64
	ds_read_b128 v[202:205], v254 offset:4608
	ds_read_b128 v[206:209], v254 offset:4672
	v_pk_mul_f32 v[82:83], v[82:83], v[180:181]
	v_pk_mul_f32 v[80:81], v[80:81], v[178:179]
	v_pk_mul_f32 v[118:119], v[118:119], v[180:181]
	v_pk_mul_f32 v[116:117], v[116:117], v[178:179]
	s_waitcnt lgkmcnt(1)
	v_mfma_f32_16x16x32_bf16 v[80:83], v[186:189], v[202:205], v[80:83]
	v_add_u32_e32 v180, v103, v129
	ds_read_b128 v[202:205], v102 offset:47872
	ds_read_b128 v[210:213], v102 offset:47936
	ds_read_b128 v[214:217], v180
	ds_read_b128 v[218:221], v180 offset:64
	s_waitcnt vmcnt(7)
	ds_bpermute_b32 v182, v124, v56
	s_waitcnt lgkmcnt(5)
	v_mfma_f32_16x16x32_bf16 v[80:83], v[190:193], v[206:209], v[80:83]
	ds_read_b128 v[206:209], v173
	ds_read_b128 v[222:225], v173 offset:64
	ds_read_b128 v[226:229], v173 offset:2304
	ds_read_b128 v[230:233], v173 offset:2368
	v_mfma_f32_16x16x32_bf16 v[116:119], v[186:189], v[194:197], v[116:119]
	s_nop 2
	v_max_f32_e64 v251, |v80|, |v80|
	v_max_f32_e32 v80, v183, v183
	s_waitcnt lgkmcnt(0)
	v_max_f32_e64 v251, |v251|, |v251|
	v_max_f32_e32 v251, v251, v252
	v_max_f32_e64 v252, |v81|, |v81|
	v_rcp_f32_e32 v251, v251
	v_mfma_f32_16x16x32_bf16 v[116:119], v[190:193], v[198:201], v[116:119]
	s_waitcnt lgkmcnt(0)
	v_max_f32_e64 v252, |v252|, |v252|
	v_max_f32_e32 v252, v252, v80
	v_rcp_f32_e32 v252, v252
	v_max_f32_e64 v80, |v82|, |v82|
	s_nop 2
	v_mul_f32_e32 v251, v116, v251
	v_cvt_pk_bf16_f32 v251, v251, s0
	ds_write_b16 v174, v251
	v_mul_f32_e32 v251, v117, v252
	v_cvt_pk_bf16_f32 v251, v251, s0
	ds_write_b16 v174, v251 offset:80
	s_waitcnt lgkmcnt(2)
	v_max_f32_e64 v251, |v80|, |v80|
	v_max_f32_e32 v252, v184, v184
	v_max_f32_e32 v251, v251, v252
	v_max_f32_e64 v252, |v83|, |v83|
	v_rcp_f32_e32 v251, v251
	v_mfma_f32_16x16x32_bf16 v[80:83], v[202:205], v[226:229], v[68:71]
	s_waitcnt lgkmcnt(0)
	v_max_f32_e64 v252, |v252|, |v252|
	s_nop 0
	v_max_f32_e32 v68, v185, v185
	v_max_f32_e32 v252, v252, v68
	v_rcp_f32_e32 v252, v252
	v_mfma_f32_16x16x32_bf16 v[76:79], v[202:205], v[214:217], v[76:79]
	v_mul_f32_e32 v251, v118, v251
	v_cvt_pk_bf16_f32 v251, v251, s0
	ds_write_b16 v174, v251 offset:160
	v_mfma_f32_16x16x32_bf16 v[72:75], v[202:205], v[206:209], v[72:75]
	v_mul_f32_e32 v251, v119, v252
	v_cvt_pk_bf16_f32 v251, v251, s0
	ds_write_b16 v174, v251 offset:240
	v_mfma_f32_16x16x32_bf16 v[76:79], v[210:213], v[218:221], v[76:79]
	v_max_f32_e32 v251, v177, v177
	v_max_f32_e32 v252, v58, v58
	v_max_f32_e32 v251, v251, v252
	v_mfma_f32_16x16x32_bf16 v[68:71], v[210:213], v[222:225], v[72:75]
	ds_bpermute_b32 v181, v124, v251
	v_mfma_f32_16x16x32_bf16 v[72:75], v[210:213], v[230:233], v[80:83]
	s_nop 2
	v_cvt_pk_bf16_f32 v80, v76, v77
	v_cvt_pk_bf16_f32 v81, v78, v79
	ds_write_b64 v175, v[80:81] offset:34816
	v_cvt_pk_bf16_f32 v80, v68, v69
	v_cvt_pk_bf16_f32 v81, v70, v71
	ds_write_b64 v176, v[80:81] offset:34816
	v_cvt_pk_bf16_f32 v80, v72, v73
	v_cvt_pk_bf16_f32 v81, v74, v75
	ds_write_b64 v176, v[80:81] offset:39168
	s_and_saveexec_b64 s[92:93], s[6:7]
	s_cbranch_execz .LBB0_456
	ds_write_b32 v133, v57
	ds_write_b32 v132, v251
.LBB0_456:
	s_or_b64 exec, exec, s[92:93]
	v_lshl_add_u64 v[120:121], s[82:83], 0, v[112:113]
	ds_write_b128 v94, v[8:11]
	ds_write_b128 v94, v[12:15] offset:17408
	ds_write_b128 v96, v[20:23]
	ds_write_b128 v96, v[24:27] offset:17408
	s_waitcnt lgkmcnt(0)
	s_barrier
	s_and_saveexec_b64 s[92:93], s[4:5]
	s_cbranch_execz .LBB0_459
	ds_read_b128 v[80:83], v134
	v_add_co_u32_e32 v116, vcc, 0x8105000, v120
	s_waitcnt lgkmcnt(0)
	v_lshlrev_b32_e32 v252, 16, v80
	v_addc_co_u32_e32 v117, vcc, 0, v121, vcc
	global_store_dwordx4 v[116:117], v[80:83], off
	v_lshlrev_b32_e32 v111, 16, v81
	v_lshlrev_b32_e32 v114, 16, v82
	v_and_b32_e32 v80, 0xffff0000, v80
	v_mul_f32_e32 v80, v80, v80
	v_fmac_f32_e32 v80, v252, v252
	v_and_b32_e32 v81, 0xffff0000, v81
	v_fmac_f32_e32 v80, v111, v111
	v_fmac_f32_e32 v80, v81, v81
	v_and_b32_e32 v82, 0xffff0000, v82
	v_fmac_f32_e32 v80, v114, v114
	v_lshlrev_b32_e32 v116, 16, v83
	v_fmac_f32_e32 v80, v82, v82
	v_and_b32_e32 v83, 0xffff0000, v83
	v_fmac_f32_e32 v80, v116, v116
	v_fmac_f32_e32 v80, v83, v83
	s_nop 1
	v_add_f32_dpp v111, v80, v80 quad_perm:[1,0,3,2] row_mask:0xf bank_mask:0xf
	s_nop 1
	v_add_f32_dpp v252, v111, v111 quad_perm:[2,3,0,1] row_mask:0xf bank_mask:0xf
	s_and_b64 exec, exec, s[10:11]
	s_cbranch_execz .LBB0_459
	v_lshl_add_u64 v[80:81], s[82:83], 0, v[108:109]
	v_add_co_u32_e32 v80, vcc, 0x29b60000, v80
	s_nop 1
	v_addc_co_u32_e32 v81, vcc, 0, v81, vcc
	global_store_dword v[80:81], v252, off

.LBB0_489:
	s_or_b64 exec, exec, s[92:93]
	v_perm_b32 v82, v251, v111, s97
	v_perm_b32 v83, v80, v81, s97
	ds_write_b64 v172, v[82:83]
	ds_read_b128 v[80:83], v100
	ds_read_b128 v[184:187], v101 offset:34816
	ds_read_b128 v[188:191], v100 offset:64
	ds_read_b128 v[192:195], v101 offset:34880
	ds_read_b128 v[196:199], v253 offset:43520
	ds_read_b128 v[200:203], v253 offset:43584
	s_waitcnt lgkmcnt(4)
	v_mfma_f32_16x16x32_bf16 v[184:187], v[80:83], v[184:187], 0
	v_add_f32_e32 v177, v181, v182
	v_pk_mul_f32 v[78:79], v[78:79], v[114:115] op_sel_hi:[1,0]
	v_pk_mul_f32 v[76:77], v[76:77], v[114:115] op_sel_hi:[1,0]
	s_waitcnt lgkmcnt(1)
	v_mfma_f32_16x16x32_bf16 v[80:83], v[80:83], v[196:199], 0
	v_mul_f32_e64 v70, v70, v114
	v_mul_f32_e64 v71, v71, v114
	v_pk_mul_f32 v[68:69], v[68:69], v[114:115] op_sel_hi:[1,0]
	v_pk_mul_f32 v[74:75], v[74:75], v[114:115] op_sel_hi:[1,0]
	v_mfma_f32_16x16x32_bf16 v[184:187], v[188:191], v[192:195], v[184:187]
	ds_read_b128 v[192:195], v100 offset:128
	ds_read_b128 v[196:199], v101 offset:34944
	v_pk_mul_f32 v[72:73], v[72:73], v[114:115] op_sel_hi:[1,0]
	s_add_i32 s72, s1, 1
	s_waitcnt lgkmcnt(2)
	v_mfma_f32_16x16x32_bf16 v[80:83], v[188:191], v[200:203], v[80:83]
	ds_read_b128 v[188:191], v253 offset:43648
	ds_read_b128 v[200:203], v100 offset:192
	ds_read_b128 v[204:207], v101 offset:35008
	s_cmpk_lt_u32 s72, 0x7f
	s_cselect_b64 s[92:93], -1, 0
	s_waitcnt lgkmcnt(3)
	v_mfma_f32_16x16x32_bf16 v[184:187], v[192:195], v[196:199], v[184:187]
	ds_read_b128 v[196:199], v253 offset:43712
	s_waitcnt lgkmcnt(0)
	s_barrier
	v_mfma_f32_16x16x32_bf16 v[80:83], v[192:195], v[188:191], v[80:83]
	ds_read_b128 v[188:191], v147
	ds_read_b128 v[192:195], v146
	s_cmpk_gt_u32 s72, 0x7e
	v_mfma_f32_16x16x32_bf16 v[80:83], v[200:203], v[196:199], v[80:83]
	ds_read_b128 v[196:199], v127
	v_mfma_f32_16x16x32_bf16 v[182:185], v[200:203], v[204:207], v[184:187]
	ds_read_b128 v[200:203], v254 offset:4608
	ds_read_b128 v[204:207], v127 offset:64
	ds_read_b128 v[208:211], v128
	ds_read_b128 v[212:215], v128 offset:64
	ds_read_b128 v[216:219], v254 offset:4672
	s_waitcnt lgkmcnt(6)
	v_pk_mul_f32 v[82:83], v[82:83], v[194:195]
	v_pk_mul_f32 v[80:81], v[80:81], v[192:193]
	v_pk_mul_f32 v[184:185], v[184:185], v[194:195]
	v_pk_mul_f32 v[182:183], v[182:183], v[192:193]
	s_waitcnt lgkmcnt(4)
	v_mfma_f32_16x16x32_bf16 v[80:83], v[196:199], v[200:203], v[80:83]
	ds_read_b128 v[192:195], v102 offset:47872
	ds_read_b128 v[200:203], v102 offset:47936
	ds_read_b128 v[220:223], v180
	ds_read_b128 v[224:227], v180 offset:64
	s_waitcnt lgkmcnt(4)
	v_mfma_f32_16x16x32_bf16 v[80:83], v[204:207], v[216:219], v[80:83]
	ds_read_b128 v[216:219], v173
	ds_read_b128 v[228:231], v173 offset:64
	ds_read_b128 v[232:235], v173 offset:2304
	ds_read_b128 v[236:239], v173 offset:2368
	v_mfma_f32_16x16x32_bf16 v[180:183], v[196:199], v[208:211], v[182:185]
	s_nop 2
	v_max_f32_e64 v251, |v80|, |v80|
	v_max_f32_e32 v80, v188, v188
	v_max_f32_e64 v111, |v83|, |v83|
	v_mfma_f32_16x16x32_bf16 v[180:183], v[204:207], v[212:215], v[180:183]
	s_waitcnt lgkmcnt(0)
	v_max_f32_e64 v251, |v251|, |v251|
	v_max_f32_e32 v251, v251, v80
	v_max_f32_e64 v80, |v81|, |v81|
	v_rcp_f32_e32 v251, v251
	v_max_f32_e32 v81, v189, v189
	v_mfma_f32_16x16x32_bf16 v[76:79], v[192:195], v[220:223], v[76:79]
	s_waitcnt lgkmcnt(0)
	v_max_f32_e64 v80, |v80|, |v80|
	v_max_f32_e32 v80, v80, v81
	v_rcp_f32_e32 v80, v80
	v_max_f32_e64 v81, |v82|, |v82|
	v_mul_f32_e32 v251, v180, v251
	v_cvt_pk_bf16_f32 v251, v251, s0
	ds_write_b16 v174, v251
	v_mul_f32_e32 v251, v181, v80
	v_cvt_pk_bf16_f32 v251, v251, s0
	ds_write_b16 v174, v251 offset:80
	s_waitcnt lgkmcnt(2)
	v_max_f32_e64 v251, |v81|, |v81|
	v_max_f32_e32 v80, v190, v190
	v_max_f32_e32 v251, v251, v80
	v_rcp_f32_e32 v251, v251
	v_mfma_f32_16x16x32_bf16 v[68:71], v[192:195], v[216:219], v[68:71]
	v_mul_f32_e32 v251, v182, v251
	v_mfma_f32_16x16x32_bf16 v[80:83], v[192:195], v[232:235], v[72:75]
	v_cvt_pk_bf16_f32 v251, v251, s0
	ds_write_b16 v174, v251 offset:160
	s_nop 0
	v_max_f32_e64 v72, |v111|, |v111|
	v_max_f32_e32 v73, v191, v191
	v_max_f32_e32 v72, v72, v73
	v_rcp_f32_e32 v111, v72
	v_mfma_f32_16x16x32_bf16 v[76:79], v[200:203], v[224:227], v[76:79]
	v_mul_f32_e32 v251, v183, v111
	v_mfma_f32_16x16x32_bf16 v[72:75], v[200:203], v[228:231], v[68:71]
	v_cvt_pk_bf16_f32 v251, v251, s0
	ds_write_b16 v174, v251 offset:240
	v_mfma_f32_16x16x32_bf16 v[68:71], v[200:203], v[236:239], v[80:83]
	s_nop 2
	v_cvt_pk_bf16_f32 v80, v76, v77
	v_cvt_pk_bf16_f32 v81, v78, v79
	ds_write_b64 v175, v[80:81] offset:34816
	v_cvt_pk_bf16_f32 v80, v72, v73
	v_cvt_pk_bf16_f32 v81, v74, v75
	ds_write_b64 v176, v[80:81] offset:34816
	v_cvt_pk_bf16_f32 v80, v68, v69
	v_cvt_pk_bf16_f32 v81, v70, v71
	ds_write_b64 v176, v[80:81] offset:39168
	s_cbranch_scc1 .LBB0_493
	s_waitcnt vmcnt(7)
	v_max_f32_e32 v251, v177, v177
	v_max_f32_e32 v252, v66, v66
	v_max_f32_e32 v81, v251, v252
	ds_bpermute_b32 v251, v124, v81
	ds_bpermute_b32 v80, v124, v64
	s_and_saveexec_b64 s[94:95], s[6:7]
	s_cbranch_execz .LBB0_492
	ds_write_b32 v133, v65
	ds_write_b32 v132, v81

.LBB0_493:
	s_waitcnt lgkmcnt(0)
	s_barrier
	s_and_saveexec_b64 s[94:95], s[4:5]
	s_cbranch_execz .LBB0_496
	ds_read_b128 v[80:83], v134
	v_add_co_u32_e32 v120, vcc, 0x8285000, v120
	s_waitcnt lgkmcnt(0)
	v_lshlrev_b32_e32 v251, 16, v80
	v_addc_co_u32_e32 v121, vcc, 0, v121, vcc
	global_store_dwordx4 v[120:121], v[80:83], off
	v_lshlrev_b32_e32 v111, 16, v81
	v_lshlrev_b32_e32 v120, 16, v82
	v_and_b32_e32 v80, 0xffff0000, v80
	v_mul_f32_e32 v80, v80, v80
	v_fmac_f32_e32 v80, v251, v251
	v_and_b32_e32 v81, 0xffff0000, v81
	v_fmac_f32_e32 v80, v111, v111
	v_fmac_f32_e32 v80, v81, v81
	v_and_b32_e32 v82, 0xffff0000, v82
	v_fmac_f32_e32 v80, v120, v120
	v_lshlrev_b32_e32 v121, 16, v83
	v_fmac_f32_e32 v80, v82, v82
	v_and_b32_e32 v83, 0xffff0000, v83
	v_fmac_f32_e32 v80, v121, v121
	v_fmac_f32_e32 v80, v83, v83
	s_nop 1
	v_add_f32_dpp v111, v80, v80 quad_perm:[1,0,3,2] row_mask:0xf bank_mask:0xf
	s_nop 1
	v_add_f32_dpp v251, v111, v111 quad_perm:[2,3,0,1] row_mask:0xf bank_mask:0xf
	s_and_b64 exec, exec, s[10:11]
	s_cbranch_execz .LBB0_496
	v_lshl_add_u64 v[80:81], s[82:83], 0, v[108:109]
	v_add_co_u32_e32 v80, vcc, 0x29b60000, v80
	s_nop 1
	v_addc_co_u32_e32 v81, vcc, 0, v81, vcc
	global_store_dword v[80:81], v251, off offset:256

.LBB0_525:
	ds_read_b128 v[106:109], v121
	ds_read_b128 v[110:113], v127 offset:34816
	ds_read_b128 v[114:117], v121 offset:64
	s_waitcnt lgkmcnt(3)
	ds_read_b128 v[148:151], v127 offset:34880
	ds_read_b128 v[156:159], v127 offset:39168
	ds_read_b128 v[160:163], v127 offset:39232
	ds_read_b128 v[166:169], v121 offset:128
	ds_read_b128 v[170:173], v127 offset:34944
	s_waitcnt lgkmcnt(6)
	v_mfma_f32_16x16x32_bf16 v[152:155], v[106:109], v[110:113], 0
	v_mov_b32_e32 v147, s56
	s_waitcnt lgkmcnt(3)
	v_mfma_f32_16x16x32_bf16 v[106:109], v[106:109], v[156:159], 0
	v_mfma_f32_16x16x32_bf16 v[152:155], v[114:117], v[148:151], v[152:155]
	s_waitcnt lgkmcnt(2)
	v_mfma_f32_16x16x32_bf16 v[106:109], v[114:117], v[160:163], v[106:109]
	ds_read_b128 v[114:117], v127 offset:39296
	ds_read_b128 v[174:177], v121 offset:192
	ds_read_b128 v[178:181], v127 offset:35008
	ds_read_b128 v[182:185], v121 offset:17408
	ds_read_b128 v[186:189], v121 offset:17472
	ds_read_b128 v[190:193], v127 offset:39360
	s_waitcnt lgkmcnt(6)
	v_mfma_f32_16x16x32_bf16 v[152:155], v[166:169], v[170:173], v[152:155]
	s_waitcnt lgkmcnt(5)
	v_mfma_f32_16x16x32_bf16 v[106:109], v[166:169], v[114:117], v[106:109]
	ds_read_b32 v147, v147
	ds_read_b128 v[166:169], v140
	ds_read_b128 v[194:197], v121 offset:17536
	ds_read_b128 v[198:201], v121 offset:17600
	ds_read_u16 v204, v141
	ds_read_u16 v205, v141 offset:144
	s_waitcnt lgkmcnt(4)
	v_sub_f32_e32 v202, v147, v166
	v_mfma_f32_16x16x32_bf16 v[110:113], v[182:185], v[110:113], 0
	v_mul_f32_e32 v202, 0x3fb8aa3b, v202
	v_mul_f32_e32 v166, 0x3fb8aa3b, v166
	v_mfma_f32_16x16x32_bf16 v[156:159], v[182:185], v[156:159], 0
	v_mfma_f32_16x16x32_bf16 v[152:155], v[174:177], v[178:181], v[152:155]
	v_mfma_f32_16x16x32_bf16 v[106:109], v[174:177], v[190:193], v[106:109]
	v_exp_f32_e32 v174, v202
	v_exp_f32_e32 v202, v166
	v_sub_f32_e32 v166, v147, v167
	v_mul_f32_e32 v167, 0x3fb8aa3b, v167
	v_exp_f32_e32 v203, v167
	v_sub_f32_e32 v167, v147, v168
	v_mfma_f32_16x16x32_bf16 v[110:113], v[186:189], v[148:151], v[110:113]
	v_mul_f32_e32 v148, 0x3fb8aa3b, v167
	v_exp_f32_e32 v167, v148
	v_mul_f32_e32 v166, 0x3fb8aa3b, v166
	v_mfma_f32_16x16x32_bf16 v[148:151], v[186:189], v[160:163], v[156:159]
	v_exp_f32_e32 v166, v166
	v_mul_f32_e32 v168, 0x3fb8aa3b, v168
	v_exp_f32_e32 v182, v168
	s_waitcnt lgkmcnt(3)
	v_mfma_f32_16x16x32_bf16 v[114:117], v[194:197], v[114:117], v[148:151]
	s_nop 2
	ds_read_u16 v150, v141 offset:288
	ds_read_u16 v151, v141 offset:432
	v_sub_f32_e32 v156, v147, v169
	v_mul_f32_e32 v156, 0x3fb8aa3b, v156
	v_exp_f32_e32 v158, v156
	s_waitcnt lgkmcnt(2)
	v_lshlrev_b32_e32 v157, 16, v205
	v_lshlrev_b32_e32 v156, 16, v204
	s_waitcnt lgkmcnt(0)
	v_lshlrev_b32_e32 v151, 16, v151
	v_lshlrev_b32_e32 v150, 16, v150
	v_pk_add_f32 v[148:149], v[156:157], v[152:153] neg_lo:[0,1] neg_hi:[0,1]
	v_pk_add_f32 v[150:151], v[150:151], v[154:155] neg_lo:[0,1] neg_hi:[0,1]
	v_mul_f32_e32 v152, v174, v148
	v_mul_f32_e32 v153, v166, v149
	v_cvt_pk_bf16_f32 v148, v148, v149
	v_mul_f32_e32 v154, v167, v150
	v_mul_f32_e32 v155, v158, v151
	v_cvt_pk_bf16_f32 v149, v150, v151
	ds_write_b64 v136, v[148:149]
	v_cvt_pk_bf16_f32 v148, v152, v153
	v_cvt_pk_bf16_f32 v149, v154, v155
	ds_write_b64 v137, v[148:149]
	ds_read_u16 v148, v142
	ds_read_u16 v149, v142 offset:144
	v_mul_f32_e32 v150, 0x3fb8aa3b, v169
	v_mfma_f32_16x16x32_bf16 v[110:113], v[194:197], v[170:173], v[110:113]
	v_exp_f32_e32 v183, v150
	ds_read_u16 v150, v142 offset:288
	ds_read_u16 v151, v142 offset:432
	s_waitcnt lgkmcnt(2)
	v_lshlrev_b32_e32 v149, 16, v149
	v_mfma_f32_16x16x32_bf16 v[110:113], v[198:201], v[178:181], v[110:113]
	v_lshlrev_b32_e32 v148, 16, v148
	v_pk_add_f32 v[106:107], v[148:149], v[106:107] neg_lo:[0,1] neg_hi:[0,1]
	s_waitcnt lgkmcnt(0)
	v_lshlrev_b32_e32 v149, 16, v151
	v_lshlrev_b32_e32 v148, 16, v150
	v_mfma_f32_16x16x32_bf16 v[114:117], v[198:201], v[190:193], v[114:117]
	v_add_f32_e64 v108, v148, -v108
	v_add_f32_e64 v109, v149, -v109
	v_mul_f32_e32 v152, v174, v106
	v_mul_f32_e32 v153, v166, v107
	v_cvt_pk_bf16_f32 v106, v106, v107
	v_mul_f32_e32 v148, v167, v108
	v_mul_f32_e32 v149, v158, v109
	v_cvt_pk_bf16_f32 v107, v108, v109
	ds_write_b64 v138, v[106:107]
	v_cvt_pk_bf16_f32 v106, v152, v153
	v_cvt_pk_bf16_f32 v107, v148, v149
	v_pk_mul_f32 v[110:111], v[110:111], v[202:203]
	v_pk_mul_f32 v[112:113], v[112:113], v[182:183]
	ds_write_b64 v139, v[106:107]
	s_waitcnt lgkmcnt(0)
	s_barrier
	ds_read_b128 v[106:109], v128
	ds_read_b128 v[148:151], v128 offset:64
	ds_read_b128 v[152:155], v129
	ds_read_b128 v[156:159], v129 offset:64
	ds_read_b128 v[160:163], v129 offset:2304
	ds_read_b128 v[166:169], v129 offset:2368
	ds_read_b128 v[170:173], v130 offset:52224
	ds_read_b128 v[174:177], v130 offset:52288
	s_waitcnt lgkmcnt(5)
	v_mfma_f32_16x16x32_bf16 v[110:113], v[106:109], v[152:155], v[110:113]
	v_mul_f32_e64 v114, v114, v202
	v_mul_f32_e64 v115, v115, v203
	v_pk_mul_f32 v[116:117], v[116:117], v[182:183]
	v_mul_f32_e32 v147, 0x3fb8aa3b, v147
	v_exp_f32_e32 v194, v147
	s_waitcnt lgkmcnt(3)
	v_mfma_f32_16x16x32_bf16 v[106:109], v[106:109], v[160:163], v[114:117]
	ds_read_b128 v[152:155], v143
	ds_read_b128 v[178:181], v143 offset:64
	s_nop 0
	ds_read_b128 v[114:117], v143 offset:2304
	ds_read_b128 v[160:163], v143 offset:2368
	ds_read_b128 v[182:185], v143 offset:4608
	ds_read_b128 v[186:189], v143 offset:4672
	v_pk_mul_f32 v[82:83], v[82:83], v[194:195] op_sel_hi:[1,0]
	v_mfma_f32_16x16x32_bf16 v[110:113], v[148:151], v[156:159], v[110:113]
	ds_read_b128 v[156:159], v143 offset:6912
	ds_read_b128 v[190:193], v143 offset:6976
	v_pk_mul_f32 v[80:81], v[80:81], v[194:195] op_sel_hi:[1,0]
	v_pk_mul_f32 v[78:79], v[78:79], v[194:195] op_sel_hi:[1,0]
	s_waitcnt lgkmcnt(10)
	v_mfma_f32_16x16x32_bf16 v[106:109], v[148:151], v[166:169], v[106:109]
	v_mul_f32_e64 v76, v76, v194
	v_mul_f32_e64 v77, v77, v194
	v_pk_mul_f32 v[70:71], v[70:71], v[194:195] op_sel_hi:[1,0]
	v_pk_mul_f32 v[68:69], v[68:69], v[194:195] op_sel_hi:[1,0]
	s_waitcnt lgkmcnt(7)
	v_mfma_f32_16x16x32_bf16 v[80:83], v[170:173], v[152:155], v[80:83]
	v_mul_f32_e64 v74, v74, v194
	v_mul_f32_e64 v75, v75, v194
	v_pk_mul_f32 v[72:73], v[72:73], v[194:195] op_sel_hi:[1,0]
	v_cvt_pk_bf16_f32 v110, v110, s0
	s_waitcnt lgkmcnt(5)
	v_mfma_f32_16x16x32_bf16 v[76:79], v[170:173], v[114:117], v[76:79]
	ds_write_b16 v144, v110
	v_cvt_pk_bf16_f32 v110, v111, s0
	ds_write_b16 v144, v110 offset:144
	s_waitcnt lgkmcnt(3)
	v_mfma_f32_16x16x32_bf16 v[114:117], v[170:173], v[156:159], v[68:71]
	s_nop 2
	v_cvt_pk_bf16_f32 v68, v112, s0
	v_mfma_f32_16x16x32_bf16 v[72:75], v[170:173], v[182:185], v[72:75]
	ds_write_b16 v144, v68 offset:288
	v_cvt_pk_bf16_f32 v68, v113, s0
	ds_write_b16 v144, v68 offset:432
	v_cvt_pk_bf16_f32 v68, v106, s0
	v_mfma_f32_16x16x32_bf16 v[80:83], v[174:177], v[178:181], v[80:83]
	ds_write_b16 v145, v68
	v_mfma_f32_16x16x32_bf16 v[68:71], v[174:177], v[160:163], v[76:79]
	s_nop 2
	v_cvt_pk_bf16_f32 v76, v107, s0
	ds_write_b16 v145, v76 offset:144
	v_cvt_pk_bf16_f32 v76, v108, s0
	v_mfma_f32_16x16x32_bf16 v[72:75], v[174:177], v[186:189], v[72:75]
	ds_write_b16 v145, v76 offset:288
	v_cvt_pk_bf16_f32 v76, v109, s0
	ds_write_b16 v145, v76 offset:432
	s_waitcnt lgkmcnt(8)
	v_mfma_f32_16x16x32_bf16 v[76:79], v[174:177], v[190:193], v[114:117]
	v_cvt_pk_bf16_f32 v106, v80, v81
	v_cvt_pk_bf16_f32 v107, v82, v83
	ds_write_b64 v146, v[106:107] offset:34816
	v_cvt_pk_bf16_f32 v106, v68, v69
	v_cvt_pk_bf16_f32 v107, v70, v71
	ds_write_b64 v146, v[106:107] offset:39168
	v_cvt_pk_bf16_f32 v106, v72, v73
	v_cvt_pk_bf16_f32 v107, v74, v75
	ds_write_b64 v146, v[106:107] offset:43520
	v_cvt_pk_bf16_f32 v106, v76, v77
	v_cvt_pk_bf16_f32 v107, v78, v79
	ds_write_b64 v146, v[106:107] offset:47872
	s_waitcnt vmcnt(8)
	ds_write_b128 v86, v[4:7]
	s_waitcnt vmcnt(7)
	ds_write_b128 v86, v[8:11] offset:17408
	s_waitcnt vmcnt(5)
	ds_write_b128 v88, v[16:19]
	s_waitcnt vmcnt(4)
	ds_write_b128 v88, v[20:23] offset:17408
	s_waitcnt vmcnt(1)
	ds_write_b128 v87, v[32:35]
	s_and_saveexec_b64 s[0:1], s[4:5]
	ds_write_b32 v135, v118
	s_or_b64 exec, exec, s[0:1]
	s_waitcnt lgkmcnt(0)
	s_barrier
	ds_read_b128 v[110:113], v131
	s_waitcnt lgkmcnt(0)
	v_and_b32_e32 v107, 0xffff0000, v110
	v_lshlrev_b32_e32 v106, 16, v110
	v_mul_f32_e32 v107, v107, v107
	v_lshlrev_b32_e32 v108, 16, v111
	v_fmac_f32_e32 v107, v106, v106
	v_and_b32_e32 v109, 0xffff0000, v111
	v_fmac_f32_e32 v107, v108, v108
	v_lshlrev_b32_e32 v114, 16, v112
	v_fmac_f32_e32 v107, v109, v109
	v_and_b32_e32 v115, 0xffff0000, v112
	v_fmac_f32_e32 v107, v114, v114
	v_lshlrev_b32_e32 v116, 16, v113
	v_fmac_f32_e32 v107, v115, v115
	v_and_b32_e32 v117, 0xffff0000, v113
	v_fmac_f32_e32 v107, v116, v116
	v_fmac_f32_e32 v107, v117, v117
	s_nop 1
	v_add_f32_dpp v108, v107, v107 quad_perm:[1,0,3,2] row_mask:0xf bank_mask:0xf
	v_lshl_add_u64 v[106:107], s[82:83], 0, v[94:95]
	v_add_co_u32_e32 v114, vcc, 0x8102000, v106
	v_add_f32_dpp v109, v108, v108 quad_perm:[2,3,0,1] row_mask:0xf bank_mask:0xf
	s_nop 0
	v_addc_co_u32_e32 v115, vcc, 0, v107, vcc
	s_nop 0
	v_add_f32_dpp v108, v109, v109 row_half_mirror row_mask:0xf bank_mask:0xf
	global_store_dwordx4 v[114:115], v[110:113], off
	v_lshl_add_u64 v[114:115], s[82:83], 0, v[104:105]
	s_and_saveexec_b64 s[0:1], s[6:7]
	s_cbranch_execz .LBB0_529
	v_mov_b32_e32 v110, v108
	v_add_co_u32_e32 v108, vcc, 0x29760000, v114
	s_nop 1
	v_addc_co_u32_e32 v109, vcc, 0, v115, vcc
	global_store_dword v[108:109], v110, off

.LBB0_537:
	s_waitcnt lgkmcnt(0)
	s_barrier
	ds_read_b128 v[150:153], v131
	s_waitcnt lgkmcnt(0)
	v_and_b32_e32 v148, 0xffff0000, v150
	v_lshlrev_b32_e32 v147, 16, v150
	v_mul_f32_e32 v148, v148, v148
	v_lshlrev_b32_e32 v149, 16, v151
	v_fmac_f32_e32 v148, v147, v147
	v_and_b32_e32 v154, 0xffff0000, v151
	v_fmac_f32_e32 v148, v149, v149
	v_lshlrev_b32_e32 v155, 16, v152
	v_fmac_f32_e32 v148, v154, v154
	v_and_b32_e32 v156, 0xffff0000, v152
	v_fmac_f32_e32 v148, v155, v155
	v_lshlrev_b32_e32 v157, 16, v153
	v_fmac_f32_e32 v148, v156, v156
	v_and_b32_e32 v158, 0xffff0000, v153
	v_fmac_f32_e32 v148, v157, v157
	v_fmac_f32_e32 v148, v158, v158
	v_add_co_u32_e32 v154, vcc, 0x8282000, v106
	s_nop 0
	v_add_f32_dpp v147, v148, v148 quad_perm:[1,0,3,2] row_mask:0xf bank_mask:0xf
	v_addc_co_u32_e32 v155, vcc, 0, v107, vcc
	s_nop 0
	v_add_f32_dpp v148, v147, v147 quad_perm:[2,3,0,1] row_mask:0xf bank_mask:0xf
	global_store_dwordx4 v[154:155], v[150:153], off
	s_nop 0
	v_add_f32_dpp v147, v148, v148 row_half_mirror row_mask:0xf bank_mask:0xf
	s_and_saveexec_b64 s[8:9], s[6:7]
	s_cbranch_execnz .LBB0_540
	s_or_b64 exec, exec, s[8:9]
	s_andn2_b64 vcc, exec, s[0:1]
	s_cbranch_vccz .LBB0_541

.LBB0_540:
	v_add_co_u32_e32 v114, vcc, 0x29760000, v114
	s_nop 1
	v_addc_co_u32_e32 v115, vcc, 0, v115, vcc
	global_store_dword v[114:115], v147, off offset:256
	s_or_b64 exec, exec, s[8:9]
	s_andn2_b64 vcc, exec, s[0:1]
	s_cbranch_vccnz .LBB0_539

	.amdhsa_kernel _Z9mk_kernelILin1EEv6Params
		.amdhsa_group_segment_fixed_size 0
		.amdhsa_private_segment_fixed_size 0
		.amdhsa_kernarg_size 416
		.amdhsa_user_sgpr_count 2
		.amdhsa_user_sgpr_dispatch_ptr 0
		.amdhsa_user_sgpr_queue_ptr 0
		.amdhsa_user_sgpr_kernarg_segment_ptr 1
		.amdhsa_user_sgpr_dispatch_id 0
		.amdhsa_user_sgpr_kernarg_preload_length 0
		.amdhsa_user_sgpr_kernarg_preload_offset 0
		.amdhsa_user_sgpr_private_segment_size 0
		.amdhsa_uses_dynamic_stack 0
		.amdhsa_enable_private_segment 0
		.amdhsa_system_sgpr_workgroup_id_x 1
		.amdhsa_system_sgpr_workgroup_id_y 0
		.amdhsa_system_sgpr_workgroup_id_z 0
		.amdhsa_system_sgpr_workgroup_info 0
		.amdhsa_system_vgpr_workitem_id 2
		.amdhsa_next_free_vgpr 255
		.amdhsa_next_free_sgpr 98
		.amdhsa_accum_offset 256
		.amdhsa_reserve_vcc 1
		.amdhsa_float_round_mode_32 0
		.amdhsa_float_round_mode_16_64 0
		.amdhsa_float_denorm_mode_32 3
		.amdhsa_float_denorm_mode_16_64 3
		.amdhsa_dx10_clamp 1
		.amdhsa_ieee_mode 1
		.amdhsa_fp16_overflow 0
		.amdhsa_tg_split 0
		.amdhsa_exception_fp_ieee_invalid_op 0
		.amdhsa_exception_fp_denorm_src 0
		.amdhsa_exception_fp_ieee_div_zero 0
		.amdhsa_exception_fp_ieee_overflow 0
		.amdhsa_exception_fp_ieee_underflow 0
		.amdhsa_exception_fp_ieee_inexact 0
		.amdhsa_exception_int_div_zero 0
	.end_amdhsa_kernel

amdhsa.kernels:
  - .agpr_count:     0
    .args:
      - .offset:         0
        .size:           160
        .value_kind:     by_value
      - .offset:         160
        .size:           4
        .value_kind:     hidden_block_count_x
      - .offset:         164
        .size:           4
        .value_kind:     hidden_block_count_y
      - .offset:         168
        .size:           4
        .value_kind:     hidden_block_count_z
      - .offset:         172
        .size:           2
        .value_kind:     hidden_group_size_x
      - .offset:         174
        .size:           2
        .value_kind:     hidden_group_size_y
      - .offset:         176
        .size:           2
        .value_kind:     hidden_group_size_z
      - .offset:         178
        .size:           2
        .value_kind:     hidden_remainder_x
      - .offset:         180
        .size:           2
        .value_kind:     hidden_remainder_y
      - .offset:         182
        .size:           2
        .value_kind:     hidden_remainder_z
      - .offset:         200
        .size:           8
        .value_kind:     hidden_global_offset_x
      - .offset:         208
        .size:           8
        .value_kind:     hidden_global_offset_y
      - .offset:         216
        .size:           8
        .value_kind:     hidden_global_offset_z
      - .offset:         224
        .size:           2
        .value_kind:     hidden_grid_dims
      - .offset:         248
        .size:           8
        .value_kind:     hidden_multigrid_sync_arg
      - .offset:         280
        .size:           4
        .value_kind:     hidden_dynamic_lds_size
    .group_segment_fixed_size: 0
    .kernarg_segment_align: 8
    .kernarg_segment_size: 416
    .language:       OpenCL C
    .language_version:
      - 2
      - 0
    .max_flat_workgroup_size: 512
    .name:           _Z9mk_kernelILin1EEv6Params
    .private_segment_fixed_size: 0
    .sgpr_count:     104
    .sgpr_spill_count: 62
    .symbol:         _Z9mk_kernelILin1EEv6Params.kd
    .uniform_work_group_size: 1
    .uses_dynamic_stack: false
    .vgpr_count:     255
    .vgpr_spill_count: 0
    .wavefront_size: 64
